# P5 work queue: next-unit ticket prefetched one unit ahead (returning atomic off the per-unit critical path)
# speedup vs baseline: 1.0076x; 1.0015x over previous
.LBB0_611:
	s_add_u32 s0, s74, 0x8001000
	s_addc_u32 s1, s75, 0
	v_writelane_b32 v234, s0, 2
	s_mov_b32 s24, 0xffec8000
	s_mov_b32 s21, 0
	v_writelane_b32 v234, s1, 3
	s_add_u32 s0, s74, 0x3b600000
	s_addc_u32 s1, s75, 0
	v_writelane_b32 v234, s0, 4
	s_add_u32 s18, s74, 0x3100
	s_addc_u32 s19, s75, 0
	v_writelane_b32 v234, s1, 5
	v_readlane_b32 s0, v235, 0
	s_lshr_b32 s30, s0, 7
	s_lshl_b32 s0, s30, 11
	s_add_i32 s34, s0, 0
	v_readlane_b32 s0, v235, 17
	s_lshl_b32 s0, s0, 2
	s_add_i32 s35, s0, 0
	s_and_b32 s31, s97, 32
	s_add_i32 s34, s34, 0x12000
	s_add_i32 s35, s35, 0x12400
	s_add_i32 s36, s97, 0x3b10
	s_add_u32 s37, s74, 0xffc9000
	s_addc_u32 s38, s75, 0
	s_or_b32 s39, s31, 0xffffffc9
	s_add_u32 s22, s74, 0x10101c00
	s_addc_u32 s23, s75, 0
	s_add_i32 s42, 0, 0x17000
	v_mov_b32_e32 v1, 0
	v_mov_b32_e32 v160, s42
	s_movk_i32 s43, 0x4e00
	s_movk_i32 s44, 0x200
	s_movk_i32 s45, 0x110
	s_movk_i32 s46, 0x90
	s_mov_b32 s47, 0xf149f2ca
	s_add_i32 s48, 0, 0x127fc
	s_mov_b32 s49, 0xefa18f08
	s_mov_b32 s25, -1
	s_mov_b32 s50, 0xf800000
	v_mov_b32_e32 v161, 0x260
	v_mov_b32_e32 v162, 0xf149f2ca
	v_mov_b32_e32 v163, 0x42000000
	v_mov_b32_e32 v164, 0x1ff
	v_mbcnt_hi_u32_b32 v182, -1, v208
	s_and_b64 vcc, exec, s[90:91]
	s_cbranch_vccnz .Lq_skip0
	s_mov_b64 s[0:1], exec
	s_mov_b64 exec, 1
	v_mov_b32_e32 v254, 0
	v_mov_b32_e32 v255, 1
	global_atomic_add v255, v254, v255, s[18:19] sc0
	s_mov_b64 exec, s[0:1]
.Lq_skip0:
	s_branch .LBB0_615

.LBB0_615:
	s_and_b64 vcc, exec, s[90:91]
	s_cbranch_vccnz .LBB0_621
	s_mov_b64 s[0:1], exec
	s_mov_b64 exec, 1
	s_waitcnt vmcnt(0)
	v_mov_b32_e32 v253, v255
	v_mov_b32_e32 v252, s42
	ds_write_b32 v252, v253
	v_mov_b32_e32 v254, 0
	v_mov_b32_e32 v255, 1
	global_atomic_add v255, v254, v255, s[18:19] sc0
	s_mov_b64 exec, s[0:1]
